# code after the first grid barrier shifted by 32 bytes (instruction-fetch alignment trial)
# baseline (speedup 1.0000x reference)
; #define PG8_STAGE(bufoff, gbase, voff) do { _Pragma("unroll") for (int _i = 0; _i < 2; ++_i) \
;         __builtin_amdgcn_global_load_lds((const unsigned*)((const char*)(gbase) + (voff)[_i]), (PG8_LAS unsigned*)(lds + (bufoff) + ldsw + _i * 8192), 16, 0, 0); } while (0)
; #define PG8_BAR __builtin_amdgcn_s_barrier()
; template <class Epi, class Sched, bool ALIGN_EPI = false, bool SP2 = false>
; __device__ __forceinline__ void gemm_phase(PG8_LAS unsigned char* lds, const Gemm g, const Sched& S, const Epi& E) {
;     ...
;     const int wid = __builtin_amdgcn_readfirstlane(tid >> 6), lane = tid & 63, wr = wid >> 2, wc = wid & 3, fr = lane & 15, fq = lane >> 4;
;     const int K = g.K, nt = K / BK;
;     unsigned voffA[2], voffB[2];
; #pragma unroll
;     for (int i = 0; i < 2; ++i) { int R, C; stage_rc(tid * 16 + i * 8192, R, C); const int Rb = Epi::PERM ? ((R & ~31) + perm32(R & 31)) : R;
;         voffA[i] = (unsigned)(R * K + C) * 2u; voffB[i] = (unsigned)(Rb * K + C) * 2u; }
;     const size_t kstep = (size_t)(BK * 2);
;     const size_t hstep = (size_t)HALF * K * 2;
;     const size_t tstep = 2 * hstep;
;     const unsigned ldsw = (unsigned)wid * 1024u;
;     const int aoff = lds_byte(wr * 64 + fr, fq * 8), boff = lds_byte(wc * 32 + fr, fq * 8);
;     ...
;     Unit cur, nxt; int ui = 0;
;     if (!S.next(0, cur)) return;
;     f32x4 acc[2][2][4][2];
; #pragma unroll
;     for (int a = 0; a < 2; ++a)
; #pragma unroll
;         for (int b = 0; b < 2; ++b)
; #pragma unroll
;             for (int m = 0; m < 4; ++m)
; #pragma unroll
;                 for (int n = 0; n < 2; ++n) acc[a][b][m][n] = (f32x4){0.f, 0.f, 0.f, 0.f};
;     bf16x8 At[4][2], B0[2][2], B1[2][2];
;     const char* cA = (const char*)g.A + (size_t)cur.pm * tstep; const char* cB = (const char*)g.Bt + (size_t)cur.pn * tstep;
;     S.a_ready(cur);
;     if constexpr (SP2) {
;         PG8_STAGE(PG8_SB(0, 0), cB, voffB); PG8_STAGE(PG8_SB(0, 1), cB + hstep, voffB); PG8_STAGE(PG8_SA(0, 0), cA, voffA); PG8_STAGE(PG8_SA(0, 1), cA + hstep, voffA);
;         if (wr == 1) PG8_BAR;
.LBB0_183:
	s_nop 0
	s_nop 0
	s_nop 0
	s_nop 0
	s_nop 0
	s_nop 0
	s_nop 0
	s_nop 0
	s_or_b64 exec, exec, s[0:1]
	v_readlane_b32 s4, v235, 8
	v_readlane_b32 s5, v235, 9
	v_and_b32_e32 v0, 7, v189
	v_lshlrev_b32_e32 v0, 3, v0
	v_add_u32_e32 v0, 0x3800, v0
	s_nop 1
	global_load_dwordx2 v[0:1], v0, s[4:5] sc1
	s_waitcnt vmcnt(0)
	v_add_u32_e32 v0, v0, v1
	v_cmp_ne_u32_e32 vcc, 17, v0
	s_cmp_lg_u64 vcc, 0
	s_cselect_b32 s4, 1, 0
	v_mov_b32_e32 v0, 0x20170
	v_mov_b32_e32 v1, s4
	ds_write_b32 v0, v1
	v_readlane_b32 s0, v235, 2
	v_readlane_b32 s2, v235, 4
	v_readlane_b32 s1, v235, 3
	v_readlane_b32 s3, v235, 5
	s_add_u32 s0, s2, 0x7000000
	s_addc_u32 s1, s3, 0
	v_writelane_b32 v235, s0, 33
	v_mov_b32_e32 v9, v189
	s_waitcnt lgkmcnt(0)
	v_writelane_b32 v235, s1, 34
	s_barrier
	v_readlane_b32 s0, v235, 0
	s_cmpk_lt_i32 s0, 0xb00
	s_cselect_b64 s[2:3], -1, 0
	v_writelane_b32 v235, s2, 35
	s_cmpk_gt_i32 s0, 0xaff
	v_readfirstlane_b32 s1, v9
	v_writelane_b32 v235, s3, 36
	s_cbranch_scc1 .LBB0_199
	v_lshlrev_b32_e32 v0, 4, v9
	v_add_u32_e32 v1, 0x2000, v0
	v_ashrrev_i32_e32 v2, 31, v1
	v_lshrrev_b32_e32 v2, 22, v2
	v_add_u32_e32 v2, v1, v2
	v_ashrrev_i32_e32 v8, 10, v2
	v_mul_i32_i24_e32 v2, 0x400, v8
	v_sub_u32_e32 v1, v1, v2
	v_lshrrev_b32_e32 v2, 4, v1
	v_bitop3_b32 v1, v2, v1, 32 bitop3:0x6c
	v_ashrrev_i32_e32 v2, 31, v1
	v_lshrrev_b32_e32 v2, 26, v2
	v_add_u32_e32 v2, v1, v2
	v_lshlrev_b32_e32 v3, 3, v8
	v_ashrrev_i32_e32 v10, 6, v2
	v_and_b32_e32 v3, -16, v3
	v_add_u32_e32 v3, v10, v3
	v_and_b32_e32 v4, 3, v10
	s_mov_b32 s0, 0x1fffe0
	v_lshrrev_b32_e32 v5, 2, v3
	v_lshlrev_b32_e32 v6, 1, v3
	v_and_b32_e32 v2, 0xc0, v2
	v_and_or_b32 v4, v3, s0, v4
	v_and_b32_e32 v5, 4, v5
	v_and_b32_e32 v6, 24, v6
	v_sub_u32_e32 v1, v1, v2
	v_mov_b32_e32 v2, 1
	v_or3_b32 v4, v4, v5, v6
	v_lshlrev_b32_e32 v5, 5, v8
	v_ashrrev_i16_sdwa v1, v2, sext(v1) dst_sel:DWORD dst_unused:UNUSED_PAD src0_sel:DWORD src1_sel:BYTE_0
	v_and_b32_e32 v5, 32, v5
	v_bfe_i32 v11, v1, 0, 16
	v_add_lshl_u32 v1, v5, v11, 1
	v_lshl_add_u32 v128, v4, 11, v1
	v_lshl_add_u32 v130, v3, 11, v1
	v_bfe_i32 v1, v9, 27, 1
	v_lshrrev_b32_e32 v1, 22, v1
	v_add_u32_e32 v1, v0, v1
	v_and_b32_e32 v1, 0xfffffc00, v1
	v_sub_u32_e32 v0, v0, v1
	v_lshrrev_b32_e32 v1, 4, v0
	v_ashrrev_i32_e32 v3, 31, v9
	v_bitop3_b32 v0, v1, v0, 32 bitop3:0x6c
	v_lshrrev_b32_e32 v3, 26, v3
	v_ashrrev_i32_e32 v1, 31, v0
	v_add_u32_e32 v3, v9, v3
	v_readlane_b32 s4, v235, 2
	v_lshrrev_b32_e32 v1, 26, v1
	v_ashrrev_i32_e32 v13, 6, v3
	v_readlane_b32 s6, v235, 4
	v_add_u32_e32 v1, v0, v1
	v_lshlrev_b32_e32 v3, 3, v13
	v_readlane_b32 s7, v235, 5
	s_add_u32 s33, s6, 0x200000
	v_ashrrev_i32_e32 v12, 6, v1
	v_and_b32_e32 v3, -16, v3
	v_readlane_b32 s3, v235, 0
	s_addc_u32 s34, s7, 0
	v_add_u32_e32 v3, v12, v3
	v_and_b32_e32 v4, 3, v12
	s_ashr_i32 s36, s3, 31
	v_and_or_b32 v4, v3, s0, v4
	s_lshr_b32 s0, s36, 29
	s_add_i32 s0, s3, s0
	s_ashr_i32 s4, s1, 6
	s_ashr_i32 s2, s0, 3
	s_and_b32 s0, s0, -8
	s_ashr_i32 s6, s1, 8
	s_lshl_b32 s35, s4, 10
	s_sub_i32 s0, s3, s0
	s_cmp_lt_i32 s0, 0
	s_movk_i32 s37, 0x161
	s_cselect_b32 s3, s37, 0x160
	s_mul_i32 s0, s0, s3
	s_add_i32 s0, s0, s2
	s_mul_hi_i32 s2, s0, 0x2e8ba2e9
	s_lshr_b32 s3, s2, 31
	s_ashr_i32 s2, s2, 4
	s_add_i32 s2, s2, s3
	s_lshl_b32 s3, s2, 2
	s_mulk_i32 s2, 0x58
	s_sub_i32 s2, s0, s2
	s_bfe_i32 s0, s2, 0x80000
	v_readlane_b32 s5, v235, 3
	s_bfe_u32 s0, s0, 0x2000d
	s_add_i32 s5, s2, s0
	s_bfe_i32 s0, s5, 0x80000
	s_and_b32 s5, s5, 0xfc
	s_sub_i32 s2, s2, s5
	s_sext_i32_i16 s0, s0
	s_sext_i32_i8 s2, s2
	v_lshrrev_b32_e32 v5, 2, v3
	v_lshlrev_b32_e32 v6, 1, v3
	v_and_b32_e32 v1, 0xc0, v1
	s_lshr_b32 s0, s0, 2
	s_add_i32 s20, s3, s2
	v_and_b32_e32 v5, 4, v5
	v_and_b32_e32 v6, 24, v6
	v_sub_u32_e32 v0, v0, v1
	s_ashr_i32 s21, s20, 31
	s_bfe_i64 s[8:9], s[0:1], 0x100000
	v_or3_b32 v4, v4, v5, v6
	v_lshlrev_b32_e32 v5, 5, v13
	v_ashrrev_i16_sdwa v0, v2, sext(v0) dst_sel:DWORD dst_unused:UNUSED_PAD src0_sel:DWORD src1_sel:BYTE_0
	s_lshl_b64 s[2:3], s[20:21], 19
	s_lshl_b64 s[8:9], s[8:9], 19
	v_and_b32_e32 v5, 32, v5
	v_bfe_i32 v14, v0, 0, 16
	s_add_u32 s24, s33, s8
	v_add_lshl_u32 v0, v5, v14, 1
	s_addc_u32 s25, s34, s9
	s_add_i32 s21, s35, 0
	v_lshl_add_u32 v132, v4, 11, v0
	s_add_i32 m0, s21, 0x10000
	v_lshl_add_u32 v134, v3, 11, v0
	global_load_lds_dwordx4 v132, s[24:25]
	s_add_i32 m0, s21, 0x12000
	s_add_u32 s8, s24, 0x40000
	global_load_lds_dwordx4 v128, s[24:25]
	s_addc_u32 s9, s25, 0
	s_add_i32 m0, s21, 0x14000
	v_mov_b32_e32 v133, 0
	global_load_lds_dwordx4 v132, s[8:9]
	s_add_i32 m0, s21, 0x16000
	v_mov_b32_e32 v129, v133
	global_load_lds_dwordx4 v128, s[8:9]
	v_readlane_b32 s8, v235, 31
	v_readlane_b32 s9, v235, 32
	s_add_u32 s22, s8, s2
	s_addc_u32 s23, s9, s3
	s_add_i32 s38, s21, 0x2000
	s_mov_b32 m0, s21
	s_add_u32 s2, s22, 0x40000
	global_load_lds_dwordx4 v134, s[22:23]
	s_mov_b32 m0, s38
	s_addc_u32 s3, s23, 0
	s_add_i32 s39, s21, 0x4000
	global_load_lds_dwordx4 v130, s[22:23]
	s_mov_b32 m0, s39
	s_add_i32 s40, s21, 0x6000
	global_load_lds_dwordx4 v134, s[2:3]
	s_mov_b32 m0, s40
	v_mov_b32_e32 v135, v133
	global_load_lds_dwordx4 v130, s[2:3]
	v_mov_b32_e32 v131, v133
	s_cmp_eq_u32 s6, 1
	s_mov_b32 s41, 0
	v_lshl_add_u64 v[6:7], s[24:25], 0, v[132:133]
	v_lshl_add_u64 v[4:5], s[24:25], 0, v[128:129]
	v_lshl_add_u64 v[0:1], s[22:23], 0, v[134:135]
	s_cselect_b64 s[2:3], -1, 0
	s_cmp_lg_u32 s6, 1
	v_lshl_add_u64 v[2:3], s[22:23], 0, v[130:131]
	s_cbranch_scc1 .LBB0_186
	s_barrier
